# nt policy also on the weight-transpose tile loads that run beside the w_in and ffn_in GEMM rounds
# speedup vs baseline: 1.0248x; 1.0037x over previous
.LBB0_163:
	s_add_i32 s0, s74, -8
	s_cmp_lt_u32 s0, -11
	v_readlane_b32 s2, v254, 28
	s_cselect_b64 s[0:1], -1, 0
	s_cmp_lt_i32 s30, s2
	s_cselect_b64 s[2:3], -1, 0
	s_or_b64 s[0:1], s[0:1], s[2:3]
	s_and_b64 vcc, exec, s[0:1]
	s_cbranch_vccnz .LBB0_171
	v_readlane_b32 s0, v254, 28
	s_sub_i32 s0, s30, s0
	s_lshl_b32 s0, s0, 1
	s_add_i32 s28, s0, s90
	v_mov_b32_e32 v0, v229
	s_cmpk_gt_i32 s28, 0x2bf
	s_cbranch_scc1 .LBB0_171
	s_mul_hi_i32 s0, s28, 0x2e8ba2e9
	s_lshr_b32 s1, s0, 31
	s_ashr_i32 s0, s0, 3
	s_add_i32 s0, s0, s1
	s_lshl_b32 s2, s0, 6
	s_mul_i32 s0, s0, 44
	v_readlane_b32 s36, v254, 46
	s_sub_i32 s0, s28, s0
	v_ashrrev_i32_e32 v34, 4, v0
	v_lshlrev_b32_e32 v1, 2, v0
	v_readlane_b32 s37, v254, 47
	s_lshl_b32 s0, s0, 6
	v_and_b32_e32 v2, 60, v1
	v_add_u32_e32 v1, s2, v34
	v_mov_b64_e32 v[4:5], s[36:37]
	s_movk_i32 s3, 0x2c00
	v_mad_i64_i32 v[6:7], s[36:37], v1, s3, v[4:5]
	s_ashr_i32 s1, s0, 31
	s_lshl_b64 s[36:37], s[0:1], 2
	v_add_u32_e32 v3, 16, v1
	v_lshl_add_u64 v[6:7], v[6:7], 0, s[36:37]
	v_lshlrev_b32_e32 v200, 2, v2
	v_mad_i64_i32 v[8:9], s[38:39], v3, s3, v[4:5]
	v_lshl_add_u64 v[6:7], v[6:7], 0, v[200:201]
	v_lshl_add_u64 v[8:9], v[8:9], 0, s[36:37]
	v_add_u32_e32 v3, 32, v1
	v_lshl_add_u64 v[8:9], v[8:9], 0, v[200:201]
	global_load_dwordx4 v[16:19], v[6:7], off nt
	global_load_dwordx4 v[20:23], v[8:9], off nt
	v_mad_i64_i32 v[6:7], s[38:39], v3, s3, v[4:5]
	v_add_u32_e32 v1, 48, v1
	v_lshl_add_u64 v[6:7], v[6:7], 0, s[36:37]
	v_mad_i64_i32 v[4:5], s[38:39], v1, s3, v[4:5]
	v_lshl_add_u64 v[6:7], v[6:7], 0, v[200:201]
	v_lshl_add_u64 v[4:5], v[4:5], 0, s[36:37]
	v_lshl_add_u64 v[4:5], v[4:5], 0, v[200:201]
	global_load_dwordx4 v[24:27], v[6:7], off nt
	global_load_dwordx4 v[28:31], v[4:5], off nt
	s_movk_i32 s1, 0x104
	v_mul_lo_u32 v1, v34, s1
	v_add3_u32 v35, s69, v1, v200
	v_lshlrev_b32_e32 v1, 3, v0
	v_and_b32_e32 v4, 56, v1
	v_ashrrev_i32_e32 v36, 3, v0
	v_mul_u32_u24_e32 v1, 0x41, v4
	v_add_u32_e32 v0, 0x100, v0
	v_readlane_b32 s3, v254, 29
	v_lshl_add_u32 v1, v1, 2, s69
	v_ashrrev_i32_e32 v38, 3, v0
	s_add_i32 s1, s3, s28
	v_mov_b32_e32 v0, 0
	v_lshl_add_u32 v37, v36, 2, v1
	v_lshl_add_u32 v39, v38, 2, v1
	s_lshl_b32 s1, s1, 6
	s_lshl_b32 s29, s3, 6
	v_lshlrev_b32_e32 v32, 2, v2
	v_lshlrev_b32_e32 v200, 1, v4
	v_mov_b32_e32 v1, v0
	v_mov_b32_e32 v2, v0
	v_mov_b32_e32 v3, v0
	v_mov_b32_e32 v4, v0
	v_mov_b32_e32 v5, v0
	v_mov_b32_e32 v6, v0
	v_mov_b32_e32 v7, v0
	v_mov_b32_e32 v8, v0
	v_mov_b32_e32 v9, v0
	v_mov_b32_e32 v10, v0
	v_mov_b32_e32 v11, v0
	v_mov_b32_e32 v12, v0
	v_mov_b32_e32 v13, v0
	v_mov_b32_e32 v14, v0
	v_mov_b32_e32 v15, v0
	s_branch .LBB0_167

.LBB0_167:
	s_waitcnt vmcnt(0)
	ds_write2_b32 v35, v16, v17 offset1:1
	ds_write2_b32 v35, v18, v19 offset0:2 offset1:3
	v_add_u32_e32 v16, 0x1040, v35
	ds_write2_b32 v16, v20, v21 offset1:1
	v_add_u32_e32 v16, 0x1048, v35
	ds_write2_b32 v16, v22, v23 offset1:1
	v_add_u32_e32 v16, 0x2080, v35
	ds_write2_b32 v16, v24, v25 offset1:1
	v_add_u32_e32 v16, 0x2088, v35
	ds_write2_b32 v16, v26, v27 offset1:1
	v_add_u32_e32 v16, 0x30c0, v35
	ds_write2_b32 v16, v28, v29 offset1:1
	v_add_u32_e32 v16, 0x30c8, v35
	v_readlane_b32 s3, v254, 29
	ds_write2_b32 v16, v30, v31 offset1:1
	s_add_i32 s28, s28, s3
	s_waitcnt lgkmcnt(0)
	s_barrier
	s_cmpk_gt_i32 s28, 0x2bf
	s_cselect_b64 s[36:37], -1, 0
	s_and_b64 vcc, exec, s[36:37]
	s_mov_b32 s38, s0
	s_mov_b32 s33, s2
	s_cbranch_vccnz .LBB0_166
	s_mul_hi_i32 s3, s28, 0x2e8ba2e9
	s_lshr_b32 s33, s3, 31
	s_ashr_i32 s3, s3, 3
	s_add_i32 s3, s3, s33
	v_readlane_b32 s40, v254, 46
	s_lshl_b32 s33, s3, 6
	s_mulk_i32 s3, 0xf500
	v_readlane_b32 s41, v254, 47
	s_add_i32 s38, s1, s3
	v_add_u32_e32 v12, s33, v34
	v_mov_b64_e32 v[8:9], s[40:41]
	s_movk_i32 s3, 0x2c00
	v_mad_i64_i32 v[0:1], s[40:41], v12, s3, v[8:9]
	s_ashr_i32 s39, s38, 31
	v_add_u32_e32 v2, 16, v12
	v_add_u32_e32 v10, 32, v12
	v_add_u32_e32 v12, 48, v12
	s_lshl_b64 s[40:41], s[38:39], 2
	v_mad_i64_i32 v[2:3], s[42:43], v2, s3, v[8:9]
	v_mad_i64_i32 v[10:11], s[42:43], v10, s3, v[8:9]
	v_mad_i64_i32 v[8:9], s[42:43], v12, s3, v[8:9]
	v_lshl_add_u64 v[0:1], v[0:1], 0, s[40:41]
	v_mov_b32_e32 v33, v201
	v_lshl_add_u64 v[2:3], v[2:3], 0, s[40:41]
	v_lshl_add_u64 v[10:11], v[10:11], 0, s[40:41]
	v_lshl_add_u64 v[8:9], v[8:9], 0, s[40:41]
	v_lshl_add_u64 v[0:1], v[0:1], 0, v[32:33]
	v_lshl_add_u64 v[4:5], v[2:3], 0, v[32:33]
	v_lshl_add_u64 v[10:11], v[10:11], 0, v[32:33]
	v_lshl_add_u64 v[12:13], v[8:9], 0, v[32:33]
	global_load_dwordx4 v[0:3], v[0:1], off nt
	s_nop 0
	global_load_dwordx4 v[4:7], v[4:5], off nt
	s_nop 0
	global_load_dwordx4 v[8:11], v[10:11], off nt
	s_nop 0
	global_load_dwordx4 v[12:15], v[12:13], off nt
	s_branch .LBB0_166

.LBB0_739:
	v_ashrrev_i32_e32 v17, 4, v18
	v_add_u32_e32 v10, s36, v17
	v_ashrrev_i32_e32 v0, 31, v10
	v_mul_lo_u32 v2, s42, v0
	v_mul_lo_u32 v3, s43, v10
	v_mad_u64_u32 v[0:1], s[44:45], s42, v10, 0
	v_add_u32_e32 v8, 32, v10
	v_add3_u32 v1, v1, v2, v3
	v_lshlrev_b32_e32 v2, 2, v18
	v_ashrrev_i32_e32 v9, 31, v8
	v_and_b32_e32 v20, 60, v2
	v_add_u32_e32 v2, 16, v10
	v_mul_lo_u32 v11, s42, v9
	v_mul_lo_u32 v12, s43, v8
	v_mad_u64_u32 v[8:9], s[46:47], s42, v8, 0
	v_add_u32_e32 v10, 48, v10
	v_ashrrev_i32_e32 v3, 31, v2
	v_add3_u32 v9, v9, v11, v12
	v_ashrrev_i32_e32 v11, 31, v10
	v_mul_lo_u32 v4, s42, v3
	v_mul_lo_u32 v5, s43, v2
	v_mad_u64_u32 v[2:3], s[46:47], s42, v2, 0
	v_mul_lo_u32 v12, s42, v11
	v_mul_lo_u32 v13, s43, v10
	v_mad_u64_u32 v[10:11], s[42:43], s42, v10, 0
	s_ashr_i32 s39, s38, 31
	v_add3_u32 v3, v3, v4, v5
	v_add3_u32 v11, v11, v12, v13
	v_lshl_add_u64 v[0:1], v[0:1], 2, s[40:41]
	s_lshl_b64 s[44:45], s[38:39], 2
	v_lshl_add_u64 v[2:3], v[2:3], 2, s[40:41]
	v_lshl_add_u64 v[8:9], v[8:9], 2, s[40:41]
	v_lshl_add_u64 v[10:11], v[10:11], 2, s[40:41]
	v_lshl_add_u64 v[0:1], v[0:1], 0, s[44:45]
	v_lshlrev_b32_e32 v200, 2, v20
	v_lshl_add_u64 v[2:3], v[2:3], 0, s[44:45]
	v_lshl_add_u64 v[8:9], v[8:9], 0, s[44:45]
	v_lshl_add_u64 v[10:11], v[10:11], 0, s[44:45]
	v_lshl_add_u64 v[0:1], v[0:1], 0, v[200:201]
	v_lshl_add_u64 v[2:3], v[2:3], 0, v[200:201]
	v_lshl_add_u64 v[8:9], v[8:9], 0, v[200:201]
	v_lshl_add_u64 v[10:11], v[10:11], 0, v[200:201]
	global_load_dwordx4 v[4:7], v[0:1], off nt
	s_nop 0
	global_load_dwordx4 v[0:3], v[2:3], off nt
	s_nop 0
	global_load_dwordx4 v[12:15], v[8:9], off nt
	s_nop 0
	global_load_dwordx4 v[8:11], v[10:11], off nt
	v_readlane_b32 s40, v253, 3
	v_readlane_b32 s52, v253, 15
	v_readlane_b32 s41, v253, 4
	v_readlane_b32 s53, v253, 16
	s_add_u32 s40, s52, s70
	v_readlane_b32 s72, v254, 57
	v_readlane_b32 s42, v253, 5
	s_addc_u32 s41, s53, s71
	v_readlane_b32 s80, v255, 1
	v_readlane_b32 s43, v253, 6
	v_readlane_b32 s81, v255, 2
	s_add_u32 s42, s80, s57
	v_readlane_b32 s44, v253, 7
	v_readlane_b32 s50, v253, 13
	s_addc_u32 s43, s81, s56
	v_readlane_b32 s45, v253, 8
	v_readlane_b32 s51, v253, 14
	s_add_u32 s44, s50, s37
	v_readlane_b32 s46, v253, 9
	v_readlane_b32 s54, v253, 17
	v_readlane_b32 s55, v253, 18
	v_readlane_b32 s78, v254, 63
	s_addc_u32 s45, s51, s33
	v_readlane_b32 s50, v255, 36
	v_readlane_b32 s47, v253, 10
	v_readlane_b32 s48, v253, 11
	v_readlane_b32 s49, v253, 12
	v_readlane_b32 s79, v255, 0
	s_add_u32 s46, s78, s70
	v_readlane_b32 s51, v255, 37
	v_readlane_b32 s52, v254, 30
	s_addc_u32 s47, s79, s71
	s_lshl_b64 s[48:49], s[50:51], 22
	v_readlane_b32 s56, v254, 34
	v_readlane_b32 s57, v254, 35
	s_add_u32 s48, s56, s48
	v_readlane_b32 s76, v254, 61
	s_addc_u32 s49, s57, s49
	s_lshl_b64 s[50:51], s[50:51], 21
	v_readlane_b32 s77, v254, 62
	s_add_u32 s50, s76, s50
	v_readlane_b32 s54, v254, 32
	s_addc_u32 s51, s77, s51
	v_readlane_b32 s53, v254, 31
	v_readlane_b32 s55, v254, 33
	s_add_u32 s52, s54, s70
	s_addc_u32 s53, s55, s71
	v_readlane_b32 s54, v255, 27
	s_add_i32 s30, s54, s30
	s_movk_i32 s39, 0x104
	s_lshl_b32 s30, s30, 3
	v_readlane_b32 s37, v255, 17
	v_mul_lo_u32 v16, v17, s39
	s_add_i32 s30, s37, s30
	s_lshl_b32 s37, s90, 2
	v_add3_u32 v28, s69, v16, v200
	v_lshlrev_b32_e32 v16, 3, v18
	s_add_i32 s30, s30, s37
	v_readlane_b32 s37, v255, 21
	v_and_b32_e32 v16, 56, v16
	s_add_i32 s37, s37, s90
	v_readlane_b32 s39, v255, 35
	v_ashrrev_i32_e32 v29, 3, v18
	v_mul_u32_u24_e32 v19, 0x41, v16
	v_add_u32_e32 v18, 0x100, v18
	v_readlane_b32 s64, v254, 42
	s_add_i32 s37, s37, s39
	v_lshl_add_u32 v19, v19, 2, s69
	v_ashrrev_i32_e32 v31, 3, v18
	v_readlane_b32 s74, v254, 59
	v_readlane_b32 s65, v254, 43
	v_readlane_b32 s66, v254, 44
	v_readlane_b32 s67, v254, 45
	v_readlane_b32 s33, v255, 20
	v_readlane_b32 s55, v255, 28
	s_lshl_b32 s64, s37, 6
	v_readlane_b32 s37, v255, 24
	v_lshl_add_u32 v30, v29, 2, v19
	v_lshl_add_u32 v32, v31, 2, v19
	s_add_i32 s33, s33, s90
	s_mov_b32 s68, s54
	s_add_i32 s65, s37, s90
	v_mov_b32_e32 v19, 0
	v_lshlrev_b32_e32 v18, 2, v20
	v_mov_b32_e32 v20, 0
	v_mov_b32_e32 v21, 0
	v_mov_b32_e32 v22, 0
	v_mov_b32_e32 v23, 0
	v_mov_b32_e32 v24, 0
	v_mov_b32_e32 v25, 0
	v_mov_b32_e32 v26, 0
	v_mov_b32_e32 v27, 0
	v_mov_b32_e32 v33, 0
	v_mov_b32_e32 v34, 0
	v_mov_b32_e32 v35, 0
	v_mov_b32_e32 v36, 0
	v_mov_b32_e32 v37, 0
	v_mov_b32_e32 v38, 0
	v_mov_b32_e32 v39, 0
	s_mov_b64 s[54:55], s[2:3]
	s_mov_b32 s67, s28
	s_mov_b32 s66, s29
	v_readlane_b32 s70, v255, 29
	v_readlane_b32 s71, v255, 30
	s_mov_b32 s74, s91
	v_readlane_b32 s73, v254, 58
	v_readlane_b32 s75, v254, 60
	v_readlane_b32 s82, v255, 3
	v_readlane_b32 s83, v255, 4
	v_readlane_b32 s84, v255, 5
	v_readlane_b32 s85, v255, 6
	v_readlane_b32 s86, v255, 7
	v_readlane_b32 s87, v255, 8
	v_readlane_b32 s58, v254, 36
	v_readlane_b32 s59, v254, 37
	v_readlane_b32 s60, v254, 38
	v_readlane_b32 s61, v254, 39
	v_readlane_b32 s62, v254, 40
	v_readlane_b32 s63, v254, 41
	s_branch .LBB0_742

.LBB0_754:
	v_add_u32_e32 v10, s72, v17
	v_ashrrev_i32_e32 v0, 31, v10
	v_add_u32_e32 v8, 32, v10
	v_mul_lo_u32 v2, s58, v0
	v_mul_lo_u32 v3, s59, v10
	v_mad_u64_u32 v[0:1], s[62:63], s58, v10, 0
	v_ashrrev_i32_e32 v9, 31, v8
	v_add3_u32 v1, v1, v2, v3
	v_add_u32_e32 v2, 16, v10
	v_mul_lo_u32 v11, s58, v9
	v_mul_lo_u32 v12, s59, v8
	v_mad_u64_u32 v[8:9], s[96:97], s58, v8, 0
	v_add_u32_e32 v10, 48, v10
	v_ashrrev_i32_e32 v3, 31, v2
	v_add3_u32 v9, v9, v11, v12
	v_ashrrev_i32_e32 v11, 31, v10
	v_mul_lo_u32 v4, s58, v3
	v_mul_lo_u32 v5, s59, v2
	v_mad_u64_u32 v[2:3], s[96:97], s58, v2, 0
	v_mul_lo_u32 v12, s58, v11
	v_mul_lo_u32 v13, s59, v10
	v_mad_u64_u32 v[10:11], s[58:59], s58, v10, 0
	s_ashr_i32 s57, s56, 31
	v_add3_u32 v3, v3, v4, v5
	v_add3_u32 v11, v11, v12, v13
	v_lshl_add_u64 v[0:1], v[0:1], 2, s[60:61]
	s_lshl_b64 s[62:63], s[56:57], 2
	v_lshl_add_u64 v[2:3], v[2:3], 2, s[60:61]
	v_lshl_add_u64 v[8:9], v[8:9], 2, s[60:61]
	v_lshl_add_u64 v[10:11], v[10:11], 2, s[60:61]
	v_lshl_add_u64 v[0:1], v[0:1], 0, s[62:63]
	v_mov_b32_e32 v19, v201
	v_lshl_add_u64 v[2:3], v[2:3], 0, s[62:63]
	v_lshl_add_u64 v[8:9], v[8:9], 0, s[62:63]
	v_lshl_add_u64 v[10:11], v[10:11], 0, s[62:63]
	v_lshl_add_u64 v[0:1], v[0:1], 0, v[18:19]
	v_lshl_add_u64 v[2:3], v[2:3], 0, v[18:19]
	v_lshl_add_u64 v[8:9], v[8:9], 0, v[18:19]
	v_lshl_add_u64 v[10:11], v[10:11], 0, v[18:19]
	global_load_dwordx4 v[4:7], v[0:1], off nt
	s_nop 0
	global_load_dwordx4 v[0:3], v[2:3], off nt
	s_nop 0
	global_load_dwordx4 v[12:15], v[8:9], off nt
	s_nop 0
	global_load_dwordx4 v[8:11], v[10:11], off nt
